# feature loop: the 32 hoisted loads are issued at the loop header, ahead of the layer-1 lower-bound loads, so both batches share one memory latency
# baseline (speedup 1.0000x reference)
; DEVI float bf2f(bf16_t h) { return __uint_as_float(((uint32_t)h) << 16); }
; DEVI void phase_p2(const int TIDX, const int BIDX, const int GDIM, KAP KA, unsigned char* WSB, float* OUTB, int l, unsigned char* smem) {
;     ...
;         float bt[16], kk[16], qv[16];
;         float bl = 0.f;
; #pragma unroll
;         for (int j = 0; j < 16; ++j) {
;           const size_t row = (size_t)ch * 32 + half * 16 + j;
;           const float z = bf2f(FQ[row * 1024 + colh]);
;           qv[j] = bf2f(FQ[row * 1024 + 512 + colh]);
;           const float e = __expf(-z);
.LBB0_376:
	s_and_b32 s9, s54, 0x180
	v_or_b32_e32 v2, s9, v17
	s_waitcnt vmcnt(24)
	v_or_b32_e32 v184, s9, v17
	v_lshlrev_b32_e32 v184, 1, v184
	v_mov_b32_e32 v185, 0
	s_ashr_i32 s44, s8, 2
	s_ashr_i32 s45, s44, 31
	s_lshl_b64 s[44:45], s[44:45], 16
	v_lshl_add_u64 v[184:185], s[42:43], 0, v[184:185]
	v_lshl_add_u64 v[184:185], v[184:185], 0, s[44:45]
	v_lshl_add_u64 v[184:185], v[184:185], 0, v[20:21]
	s_mov_b64 s[44:45], 0x2000
	v_lshl_add_u64 v[176:177], v[184:185], 0, s[44:45]
	s_mov_b64 s[44:45], 0x4000
	v_lshl_add_u64 v[178:179], v[184:185], 0, s[44:45]
	s_mov_b64 s[44:45], 0x6000
	v_lshl_add_u64 v[180:181], v[184:185], 0, s[44:45]
	s_mov_b64 s[44:45], 0x8000
	v_lshl_add_u64 v[182:183], v[184:185], 0, s[44:45]
	global_load_ushort v142, v[184:185], off
	global_load_ushort v143, v[184:185], off offset:1024
	global_load_ushort v144, v[184:185], off offset:2048
	global_load_ushort v145, v[184:185], off offset:3072
	global_load_ushort v146, v[176:177], off offset:-4096
	global_load_ushort v147, v[176:177], off offset:-3072
	global_load_ushort v148, v[176:177], off offset:-2048
	global_load_ushort v149, v[176:177], off offset:-1024
	global_load_ushort v150, v[176:177], off
	global_load_ushort v151, v[176:177], off offset:1024
	global_load_ushort v152, v[176:177], off offset:2048
	global_load_ushort v153, v[176:177], off offset:3072
	global_load_ushort v154, v[178:179], off offset:-4096
	global_load_ushort v155, v[178:179], off offset:-3072
	global_load_ushort v156, v[178:179], off offset:-2048
	global_load_ushort v157, v[178:179], off offset:-1024
	global_load_ushort v158, v[178:179], off
	global_load_ushort v159, v[178:179], off offset:1024
	global_load_ushort v160, v[178:179], off offset:2048
	global_load_ushort v162, v[178:179], off offset:3072
	global_load_ushort v163, v[180:181], off offset:-4096
	global_load_ushort v164, v[180:181], off offset:-3072
	global_load_ushort v165, v[180:181], off offset:-2048
	global_load_ushort v166, v[180:181], off offset:-1024
	global_load_ushort v167, v[180:181], off
	global_load_ushort v168, v[180:181], off offset:1024
	global_load_ushort v169, v[180:181], off offset:2048
	global_load_ushort v170, v[180:181], off offset:3072
	global_load_ushort v171, v[182:183], off offset:-4096
	global_load_ushort v172, v[182:183], off offset:-3072
	global_load_ushort v173, v[182:183], off offset:-2048
	global_load_ushort v174, v[182:183], off offset:-1024
	s_andn2_b64 vcc, exec, s[0:1]
	s_mov_b64 s[44:45], -1
	s_cbranch_vccnz .LBB0_378
	s_mov_b64 s[44:45], 0

; DEVI float bf2f(bf16_t h) { return __uint_as_float(((uint32_t)h) << 16); }
; DEVI void phase_p2(const int TIDX, const int BIDX, const int GDIM, KAP KA, unsigned char* WSB, float* OUTB, int l, unsigned char* smem) {
;     ...
;         float bt[16], kk[16], qv[16];
;         float bl = 0.f;
; #pragma unroll
;         for (int j = 0; j < 16; ++j) {
;           const size_t row = (size_t)ch * 32 + half * 16 + j;
;           const float z = bf2f(FQ[row * 1024 + colh]);
;           qv[j] = bf2f(FQ[row * 1024 + 512 + colh]);
;           const float e = __expf(-z);
;           const float inv = __builtin_amdgcn_rcpf(1.f + e);
;           const float f = lb + oml * inv;
;           kk[j] = oml * e * inv;
;           bl += __logf(f);
;           bt[j] = bl;
;         }
.LBB0_380:
	s_ashr_i32 s44, s8, 2
	s_ashr_i32 s45, s44, 31
	v_lshlrev_b32_e32 v128, 1, v2
	v_lshl_add_u64 v[2:3], s[42:43], 0, v[128:129]
	s_lshl_b64 s[44:45], s[44:45], 16
	v_lshl_add_u64 v[2:3], v[2:3], 0, s[44:45]
	v_lshl_add_u64 v[46:47], v[2:3], 0, v[20:21]
	s_nop 0
	s_nop 0
	v_sub_f32_e32 v0, 1.0, v51
	s_mov_b32 s75, 0x3f317217
	s_mov_b32 s74, 0x7f800000
	s_movk_i32 s9, 0x1000
	s_waitcnt vmcnt(31)
	v_mov_b32_e32 v1, v142
	v_lshlrev_b32_e32 v1, 16, v1
	v_mul_f32_e32 v1, 0xbfb8aa3b, v1
	v_exp_f32_e32 v8, v1
	s_waitcnt vmcnt(30)
	v_mov_b32_e32 v2, v143
	v_lshlrev_b32_e32 v56, 16, v2
	v_add_f32_e32 v1, 1.0, v8
	v_rcp_f32_e32 v6, v1
	s_nop 0
	v_fma_f32 v1, v0, v6, v51
	v_cmp_gt_f32_e32 vcc, s60, v1
	s_nop 1
	v_cndmask_b32_e64 v2, 0, 32, vcc
	v_ldexp_f32 v1, v1, v2
	v_log_f32_e32 v1, v1
	s_nop 0
	v_mul_f32_e32 v2, 0x3f317217, v1
	v_fma_f32 v2, v1, s75, -v2
	v_fmac_f32_e32 v2, 0x3377d1cf, v1
	v_fmac_f32_e32 v2, 0x3f317217, v1
	v_cmp_lt_f32_e64 s[44:45], |v1|, s74
	s_nop 1
	v_cndmask_b32_e64 v1, v1, v2, s[44:45]
	v_cndmask_b32_e32 v2, 0, v235, vcc
	v_sub_f32_e32 v1, v1, v2
	v_add_f32_e32 v57, 0, v1
	s_nop 0
	s_nop 0
	s_waitcnt vmcnt(29)
	v_mov_b32_e32 v1, v144
	v_lshlrev_b32_e32 v1, 16, v1
	v_mul_f32_e32 v1, 0xbfb8aa3b, v1
	v_exp_f32_e32 v9, v1
	s_waitcnt vmcnt(28)
	v_mov_b32_e32 v2, v145
	v_lshlrev_b32_e32 v79, 16, v2
	v_mul_f32_e32 v103, 0xbfb8aa3b, v79
	v_exp_f32_e32 v103, v103
	v_add_f32_e32 v1, 1.0, v9
	v_rcp_f32_e32 v7, v1
	v_add_f32_e32 v103, 1.0, v103
	v_rcp_f32_e32 v103, v103
	v_fma_f32 v1, v0, v7, v51
	v_cmp_gt_f32_e32 vcc, s60, v1
	v_mul_f32_e32 v79, v103, v79
	s_nop 0
	v_cndmask_b32_e64 v2, 0, 32, vcc
	v_ldexp_f32 v1, v1, v2
	v_log_f32_e32 v1, v1
	s_nop 0
	v_mul_f32_e32 v2, 0x3f317217, v1
	v_fma_f32 v2, v1, s75, -v2
	v_fmac_f32_e32 v2, 0x3377d1cf, v1
	v_fmac_f32_e32 v2, 0x3f317217, v1
	v_cmp_lt_f32_e64 s[44:45], |v1|, s74
	s_nop 1
	v_cndmask_b32_e64 v1, v1, v2, s[44:45]
	v_cndmask_b32_e32 v2, 0, v235, vcc
	v_sub_f32_e32 v1, v1, v2
	v_add_co_u32_e32 v2, vcc, s9, v46
	s_movk_i32 s9, 0x2000
	s_nop 0
	v_addc_co_u32_e32 v3, vcc, 0, v47, vcc
	v_add_co_u32_e32 v4, vcc, s9, v46
	v_add_f32_e32 v86, v57, v1
	s_nop 0
	v_addc_co_u32_e32 v5, vcc, 0, v47, vcc
	s_nop 0
	s_nop 0
	s_movk_i32 s9, 0x3000
	s_waitcnt vmcnt(27)
	v_mov_b32_e32 v1, v146
	v_lshlrev_b32_e32 v1, 16, v1
	v_mul_f32_e32 v1, 0xbfb8aa3b, v1
	v_exp_f32_e32 v36, v1
	s_waitcnt vmcnt(26)
	v_mov_b32_e32 v10, v147
	v_lshlrev_b32_e32 v83, 16, v10
	v_add_f32_e32 v1, 1.0, v36
	v_rcp_f32_e32 v34, v1
	s_nop 0
	v_fma_f32 v1, v0, v34, v51
	v_cmp_gt_f32_e32 vcc, s60, v1
	s_nop 1
	v_cndmask_b32_e64 v10, 0, 32, vcc
	v_ldexp_f32 v1, v1, v10
	v_log_f32_e32 v1, v1
	s_nop 0
	v_mul_f32_e32 v10, 0x3f317217, v1
	v_fma_f32 v10, v1, s75, -v10
	v_fmac_f32_e32 v10, 0x3377d1cf, v1
	v_fmac_f32_e32 v10, 0x3f317217, v1
	v_cmp_lt_f32_e64 s[44:45], |v1|, s74
	s_nop 1
	v_cndmask_b32_e64 v1, v1, v10, s[44:45]
	v_cndmask_b32_e32 v10, 0, v235, vcc
	v_sub_f32_e32 v1, v1, v10
	v_add_f32_e32 v89, v86, v1
	s_nop 0
	s_waitcnt vmcnt(25)
	v_mov_b32_e32 v1, v148
	v_lshlrev_b32_e32 v1, 16, v1
	s_nop 0
	v_mul_f32_e32 v1, 0xbfb8aa3b, v1
	v_exp_f32_e32 v37, v1
	s_waitcnt vmcnt(24)
	v_mov_b32_e32 v2, v149
	v_lshlrev_b32_e32 v88, 16, v2
	v_add_f32_e32 v1, 1.0, v37
	v_rcp_f32_e32 v35, v1
	s_nop 0
	v_fma_f32 v1, v0, v35, v51
	v_cmp_gt_f32_e32 vcc, s60, v1
	s_nop 1
	v_cndmask_b32_e64 v2, 0, 32, vcc
	v_ldexp_f32 v1, v1, v2
	v_log_f32_e32 v1, v1
	s_nop 0
	v_mul_f32_e32 v2, 0x3f317217, v1
	v_fma_f32 v2, v1, s75, -v2
	v_fmac_f32_e32 v2, 0x3377d1cf, v1
	v_fmac_f32_e32 v2, 0x3f317217, v1
	v_cmp_lt_f32_e64 s[44:45], |v1|, s74
	s_nop 1
	v_cndmask_b32_e64 v1, v1, v2, s[44:45]
	v_cndmask_b32_e32 v2, 0, v235, vcc
	v_sub_f32_e32 v1, v1, v2
	v_add_f32_e32 v92, v89, v1
	s_nop 0
	s_nop 0
	s_waitcnt vmcnt(23)
	v_mov_b32_e32 v1, v150
	v_lshlrev_b32_e32 v1, 16, v1
	v_mul_f32_e32 v1, 0xbfb8aa3b, v1
	v_exp_f32_e32 v32, v1
	s_waitcnt vmcnt(22)
	v_mov_b32_e32 v2, v151
	v_lshlrev_b32_e32 v81, 16, v2
	v_add_f32_e32 v1, 1.0, v32
	v_rcp_f32_e32 v14, v1
	s_nop 0
	v_fma_f32 v1, v0, v14, v51
	v_cmp_gt_f32_e32 vcc, s60, v1
	s_nop 1
	v_cndmask_b32_e64 v2, 0, 32, vcc
	v_ldexp_f32 v1, v1, v2
	v_log_f32_e32 v1, v1
	s_nop 0
	v_mul_f32_e32 v2, 0x3f317217, v1
	v_fma_f32 v2, v1, s75, -v2
	v_fmac_f32_e32 v2, 0x3377d1cf, v1
	v_fmac_f32_e32 v2, 0x3f317217, v1
	v_cmp_lt_f32_e64 s[44:45], |v1|, s74
	s_nop 1
	v_cndmask_b32_e64 v1, v1, v2, s[44:45]
	v_cndmask_b32_e32 v2, 0, v235, vcc
	v_sub_f32_e32 v1, v1, v2
	v_add_f32_e32 v87, v92, v1
	s_nop 0
	s_nop 0
	s_waitcnt vmcnt(21)
	v_mov_b32_e32 v1, v152
	v_lshlrev_b32_e32 v1, 16, v1
	v_mul_f32_e32 v1, 0xbfb8aa3b, v1
	v_exp_f32_e32 v33, v1
	s_waitcnt vmcnt(20)
	v_mov_b32_e32 v2, v153
	v_lshlrev_b32_e32 v77, 16, v2
	v_add_f32_e32 v1, 1.0, v33
	v_rcp_f32_e32 v15, v1
	s_nop 0
	v_fma_f32 v1, v0, v15, v51
	v_cmp_gt_f32_e32 vcc, s60, v1
	s_nop 1
	v_cndmask_b32_e64 v2, 0, 32, vcc
	v_ldexp_f32 v1, v1, v2
	v_log_f32_e32 v1, v1
	s_nop 0
	v_mul_f32_e32 v2, 0x3f317217, v1
	v_fma_f32 v2, v1, s75, -v2
	v_fmac_f32_e32 v2, 0x3377d1cf, v1
	v_fmac_f32_e32 v2, 0x3f317217, v1
	v_cmp_lt_f32_e64 s[44:45], |v1|, s74
	s_nop 1
	v_cndmask_b32_e64 v1, v1, v2, s[44:45]
	v_cndmask_b32_e32 v2, 0, v235, vcc
	v_sub_f32_e32 v1, v1, v2
	v_add_co_u32_e32 v2, vcc, s9, v46
	s_movk_i32 s9, 0x4000
	s_nop 0
	v_addc_co_u32_e32 v3, vcc, 0, v47, vcc
	v_add_co_u32_e32 v4, vcc, s9, v46
	v_add_f32_e32 v82, v87, v1
	s_nop 0
	v_addc_co_u32_e32 v5, vcc, 0, v47, vcc
	s_nop 0
	s_nop 0
	s_movk_i32 s9, 0x5000
	s_waitcnt vmcnt(19)
	v_mov_b32_e32 v1, v154
	v_lshlrev_b32_e32 v1, 16, v1
	v_mul_f32_e32 v1, 0xbfb8aa3b, v1
	v_exp_f32_e32 v44, v1
	s_waitcnt vmcnt(18)
; DEVI float bf2f(bf16_t h) { return __uint_as_float(((uint32_t)h) << 16); }
; DEVI void phase_p2(const int TIDX, const int BIDX, const int GDIM, KAP KA, unsigned char* WSB, float* OUTB, int l, unsigned char* smem) {
;     ...
;         for (int j = 0; j < 16; ++j) {
;           const size_t row = (size_t)ch * 32 + half * 16 + j;
;           const float z = bf2f(FQ[row * 1024 + colh]);
;           qv[j] = bf2f(FQ[row * 1024 + 512 + colh]);
;           const float e = __expf(-z);
;           const float inv = __builtin_amdgcn_rcpf(1.f + e);
;           const float f = lb + oml * inv;
;           kk[j] = oml * e * inv;
;           bl += __logf(f);
;           bt[j] = bl;
;         }
	v_mov_b32_e32 v10, v155
	v_lshlrev_b32_e32 v95, 16, v10
	v_add_f32_e32 v1, 1.0, v44
	v_rcp_f32_e32 v42, v1
	s_nop 0
	v_fma_f32 v1, v0, v42, v51
	v_cmp_gt_f32_e32 vcc, s60, v1
	s_nop 1
	v_cndmask_b32_e64 v10, 0, 32, vcc
	v_ldexp_f32 v1, v1, v10
	v_log_f32_e32 v1, v1
	s_nop 0
	v_mul_f32_e32 v10, 0x3f317217, v1
	v_fma_f32 v10, v1, s75, -v10
	v_fmac_f32_e32 v10, 0x3377d1cf, v1
	v_fmac_f32_e32 v10, 0x3f317217, v1
	v_cmp_lt_f32_e64 s[44:45], |v1|, s74
	s_nop 1
	v_cndmask_b32_e64 v1, v1, v10, s[44:45]
	v_cndmask_b32_e32 v10, 0, v235, vcc
	v_sub_f32_e32 v1, v1, v10
	v_add_f32_e32 v97, v82, v1
	s_nop 0
	s_waitcnt vmcnt(17)
	v_mov_b32_e32 v1, v156
	v_lshlrev_b32_e32 v1, 16, v1
	s_nop 0
	v_mul_f32_e32 v1, 0xbfb8aa3b, v1
	v_exp_f32_e32 v45, v1
	s_waitcnt vmcnt(16)
	v_mov_b32_e32 v2, v157
	v_lshlrev_b32_e32 v94, 16, v2
	v_add_f32_e32 v1, 1.0, v45
	v_rcp_f32_e32 v43, v1
	s_nop 0
	v_fma_f32 v1, v0, v43, v51
	v_cmp_gt_f32_e32 vcc, s60, v1
	s_nop 1
	v_cndmask_b32_e64 v2, 0, 32, vcc
	v_ldexp_f32 v1, v1, v2
	v_log_f32_e32 v1, v1
	s_nop 0
	v_mul_f32_e32 v2, 0x3f317217, v1
	v_fma_f32 v2, v1, s75, -v2
	v_fmac_f32_e32 v2, 0x3377d1cf, v1
	v_fmac_f32_e32 v2, 0x3f317217, v1
	v_cmp_lt_f32_e64 s[44:45], |v1|, s74
	s_nop 1
	v_cndmask_b32_e64 v1, v1, v2, s[44:45]
	v_cndmask_b32_e32 v2, 0, v235, vcc
	v_sub_f32_e32 v1, v1, v2
	v_add_f32_e32 v96, v97, v1
	s_nop 0
	s_nop 0
	s_waitcnt vmcnt(15)
	v_mov_b32_e32 v1, v158
	v_lshlrev_b32_e32 v1, 16, v1
	v_mul_f32_e32 v1, 0xbfb8aa3b, v1
	v_exp_f32_e32 v40, v1
	s_waitcnt vmcnt(14)
	v_mov_b32_e32 v2, v159
	v_lshlrev_b32_e32 v90, 16, v2
	v_add_f32_e32 v1, 1.0, v40
	v_rcp_f32_e32 v38, v1
	s_nop 0
	v_fma_f32 v1, v0, v38, v51
	v_cmp_gt_f32_e32 vcc, s60, v1
	s_nop 1
	v_cndmask_b32_e64 v2, 0, 32, vcc
	v_ldexp_f32 v1, v1, v2
	v_log_f32_e32 v1, v1
	s_nop 0
	v_mul_f32_e32 v2, 0x3f317217, v1
	v_fma_f32 v2, v1, s75, -v2
	v_fmac_f32_e32 v2, 0x3377d1cf, v1
	v_fmac_f32_e32 v2, 0x3f317217, v1
	v_cmp_lt_f32_e64 s[44:45], |v1|, s74
	s_nop 1
	v_cndmask_b32_e64 v1, v1, v2, s[44:45]
	v_cndmask_b32_e32 v2, 0, v235, vcc
	v_sub_f32_e32 v1, v1, v2
	v_add_f32_e32 v93, v96, v1
	s_nop 0
	s_nop 0
	s_waitcnt vmcnt(13)
	v_mov_b32_e32 v1, v160
	v_lshlrev_b32_e32 v1, 16, v1
	v_mul_f32_e32 v1, 0xbfb8aa3b, v1
	v_exp_f32_e32 v41, v1
	s_waitcnt vmcnt(12)
	v_mov_b32_e32 v2, v162
	v_lshlrev_b32_e32 v84, 16, v2
	v_add_f32_e32 v1, 1.0, v41
	v_rcp_f32_e32 v39, v1
	s_nop 0
	v_fma_f32 v1, v0, v39, v51
	v_cmp_gt_f32_e32 vcc, s60, v1
	s_nop 1
	v_cndmask_b32_e64 v2, 0, 32, vcc
	v_ldexp_f32 v1, v1, v2
	v_log_f32_e32 v1, v1
	s_nop 0
	v_mul_f32_e32 v2, 0x3f317217, v1
	v_fma_f32 v2, v1, s75, -v2
	v_fmac_f32_e32 v2, 0x3377d1cf, v1
	v_fmac_f32_e32 v2, 0x3f317217, v1
	v_cmp_lt_f32_e64 s[44:45], |v1|, s74
	s_nop 1
	v_cndmask_b32_e64 v1, v1, v2, s[44:45]
	v_cndmask_b32_e32 v2, 0, v235, vcc
	v_sub_f32_e32 v1, v1, v2
	v_add_co_u32_e32 v2, vcc, s9, v46
	s_movk_i32 s9, 0x6000
	s_nop 0
	v_addc_co_u32_e32 v3, vcc, 0, v47, vcc
	v_add_co_u32_e32 v48, vcc, s9, v46
	v_add_f32_e32 v91, v93, v1
	s_nop 0
	v_addc_co_u32_e32 v49, vcc, 0, v47, vcc
	s_nop 0
	s_nop 0
	s_movk_i32 s9, 0x7000
	s_waitcnt vmcnt(11)
	v_mov_b32_e32 v1, v163
	v_lshlrev_b32_e32 v1, 16, v1
	v_mul_f32_e32 v1, 0xbfb8aa3b, v1
	v_exp_f32_e32 v12, v1
	s_waitcnt vmcnt(10)
	v_mov_b32_e32 v4, v164
	v_lshlrev_b32_e32 v78, 16, v4
	v_add_f32_e32 v1, 1.0, v12
	v_rcp_f32_e32 v10, v1
	s_nop 0
	v_fma_f32 v1, v0, v10, v51
	v_cmp_gt_f32_e32 vcc, s60, v1
	s_nop 1
	v_cndmask_b32_e64 v4, 0, 32, vcc
	v_ldexp_f32 v1, v1, v4
	v_log_f32_e32 v1, v1
	s_nop 0
	v_mul_f32_e32 v4, 0x3f317217, v1
	v_fma_f32 v4, v1, s75, -v4
	v_fmac_f32_e32 v4, 0x3377d1cf, v1
	v_fmac_f32_e32 v4, 0x3f317217, v1
	v_cmp_lt_f32_e64 s[44:45], |v1|, s74
	s_nop 1
	v_cndmask_b32_e64 v1, v1, v4, s[44:45]
	v_cndmask_b32_e32 v4, 0, v235, vcc
	v_sub_f32_e32 v1, v1, v4
	v_add_f32_e32 v85, v91, v1
	s_nop 0
	s_waitcnt vmcnt(9)
	v_mov_b32_e32 v1, v165
	v_lshlrev_b32_e32 v1, 16, v1
	s_nop 0
	v_mul_f32_e32 v1, 0xbfb8aa3b, v1
	v_exp_f32_e32 v13, v1
	s_waitcnt vmcnt(8)
	v_mov_b32_e32 v2, v166
	v_lshlrev_b32_e32 v76, 16, v2
	v_add_f32_e32 v1, 1.0, v13
	v_rcp_f32_e32 v11, v1
	s_nop 0
	v_fma_f32 v1, v0, v11, v51
	v_cmp_gt_f32_e32 vcc, s60, v1
	s_nop 1
	v_cndmask_b32_e64 v2, 0, 32, vcc
	v_ldexp_f32 v1, v1, v2
	v_log_f32_e32 v1, v1
	s_nop 0
	v_mul_f32_e32 v2, 0x3f317217, v1
	v_fma_f32 v2, v1, s75, -v2
	v_fmac_f32_e32 v2, 0x3377d1cf, v1
	v_fmac_f32_e32 v2, 0x3f317217, v1
	v_cmp_lt_f32_e64 s[44:45], |v1|, s74
	s_nop 1
	v_cndmask_b32_e64 v1, v1, v2, s[44:45]
	v_cndmask_b32_e32 v2, 0, v235, vcc
	v_sub_f32_e32 v1, v1, v2
	v_add_f32_e32 v80, v85, v1
	s_nop 0
	s_nop 0
	s_waitcnt vmcnt(7)
	v_mov_b32_e32 v1, v167
	v_lshlrev_b32_e32 v1, 16, v1
	v_mul_f32_e32 v1, 0xbfb8aa3b, v1
	v_exp_f32_e32 v4, v1
	s_waitcnt vmcnt(6)
	v_mov_b32_e32 v2, v168
	v_lshlrev_b32_e32 v19, 16, v2
	v_add_f32_e32 v1, 1.0, v4
	v_rcp_f32_e32 v2, v1
	s_nop 0
	v_fma_f32 v1, v0, v2, v51
	v_cmp_gt_f32_e32 vcc, s60, v1
	s_nop 1
	v_cndmask_b32_e64 v3, 0, 32, vcc
	v_ldexp_f32 v1, v1, v3
	v_log_f32_e32 v1, v1
	s_nop 0
	v_mul_f32_e32 v3, 0x3f317217, v1
	v_fma_f32 v3, v1, s75, -v3
	v_fmac_f32_e32 v3, 0x3377d1cf, v1
	v_fmac_f32_e32 v3, 0x3f317217, v1
	v_cmp_lt_f32_e64 s[44:45], |v1|, s74
	s_nop 1
	v_cndmask_b32_e64 v1, v1, v3, s[44:45]
	v_cndmask_b32_e32 v3, 0, v235, vcc
	v_sub_f32_e32 v1, v1, v3
	v_add_f32_e32 v52, v80, v1
	s_nop 0
	s_waitcnt vmcnt(5)
	v_mov_b32_e32 v1, v169
	v_lshlrev_b32_e32 v3, 16, v1
	v_mul_f32_e32 v3, 0xbfb8aa3b, v3
	v_exp_f32_e32 v5, v3
	s_nop 0
	v_add_f32_e32 v3, 1.0, v5
	v_rcp_f32_e32 v3, v3
	s_waitcnt vmcnt(4)
; DEVI float bf2f(bf16_t h) { return __uint_as_float(((uint32_t)h) << 16); }
; DEVI bf16_t f2bf(float f) { uint32_t u = __float_as_uint(f); u += 0x7fffu + ((u >> 16) & 1u); return (bf16_t)(u >> 16); }
; DEVI void phase_p2(const int TIDX, const int BIDX, const int GDIM, KAP KA, unsigned char* WSB, float* OUTB, int l, unsigned char* smem) {
;     ...
;         for (int j = 0; j < 16; ++j) {
;           const size_t row = (size_t)ch * 32 + half * 16 + j;
;           const float z = bf2f(FQ[row * 1024 + colh]);
;           qv[j] = bf2f(FQ[row * 1024 + 512 + colh]);
;           const float e = __expf(-z);
;           const float inv = __builtin_amdgcn_rcpf(1.f + e);
;           const float f = lb + oml * inv;
;           kk[j] = oml * e * inv;
;           bl += __logf(f);
;           bt[j] = bl;
;         }
;         sB[half * 128 + k] = bl;
;         __syncthreads();
;         const float b0 = sB[k], b1 = sB[128 + k];
;         const float off = half ? b0 : 0.f, bend = b0 + b1;
;         uint32_t pk[8];
; #pragma unroll
;         for (int j = 0; j < 16; ++j) {
;           const int t = half * 16 + j;
;           const float b = bt[j] + off;
;           const float qs = qv[j] * __builtin_amdgcn_rcpf(1.f + __expf(-qv[j]));
;           const bf16_t qt = f2bf(qs * __expf(b));
;           QT[((size_t)cid * 32 + t) * 128 + k] = qt;
;           sQ[t * 136 + k] = qt;
;           sK[t * 136 + k] = f2bf(kk[j] * __expf(fminf(-b, 80.f)));
;           bt[j] = kk[j] * __expf(bend - b);
	v_mov_b32_e32 v1, v170
	v_lshlrev_b32_e32 v1, 16, v1
	v_fma_f32 v48, v0, v3, v51
	v_cmp_gt_f32_e32 vcc, s60, v48
	v_pk_mul_f32 v[8:9], v[0:1], v[8:9] op_sel_hi:[0,1]
	v_pk_mul_f32 v[6:7], v[8:9], v[6:7]
	v_cndmask_b32_e64 v49, 0, 32, vcc
	v_ldexp_f32 v48, v48, v49
	v_log_f32_e32 v48, v48
	v_pk_mul_f32 v[32:33], v[0:1], v[32:33] op_sel_hi:[0,1]
	v_pk_mul_f32 v[14:15], v[32:33], v[14:15]
	v_pk_mul_f32 v[12:13], v[0:1], v[12:13] op_sel_hi:[0,1]
	v_mul_f32_e32 v49, 0x3f317217, v48
	v_fma_f32 v49, v48, s75, -v49
	v_fmac_f32_e32 v49, 0x3377d1cf, v48
	v_fmac_f32_e32 v49, 0x3f317217, v48
	v_cmp_lt_f32_e64 s[44:45], |v48|, s74
	v_pk_mul_f32 v[10:11], v[12:13], v[10:11]
	s_nop 0
	v_cndmask_b32_e64 v48, v48, v49, s[44:45]
	v_cndmask_b32_e32 v49, 0, v235, vcc
	v_add_co_u32_e32 v54, vcc, s9, v46
	v_sub_f32_e32 v48, v48, v49
	s_nop 0
	v_addc_co_u32_e32 v55, vcc, 0, v47, vcc
	s_nop 0
	s_nop 0
	v_add_f32_e32 v50, v52, v48
	s_mov_b32 s9, 0x42a00000
	s_waitcnt vmcnt(3)
	v_mov_b32_e32 v46, v171
	v_lshlrev_b32_e32 v46, 16, v46
	v_mul_f32_e32 v46, 0xbfb8aa3b, v46
	v_exp_f32_e32 v48, v46
	s_waitcnt vmcnt(2)
	v_mov_b32_e32 v47, v172
	v_lshlrev_b32_e32 v98, 16, v47
	v_add_f32_e32 v46, 1.0, v48
	v_rcp_f32_e32 v46, v46
	s_nop 0
	v_fma_f32 v47, v0, v46, v51
	v_cmp_gt_f32_e32 vcc, s60, v47
	s_nop 1
	v_cndmask_b32_e64 v49, 0, 32, vcc
	v_ldexp_f32 v47, v47, v49
	v_log_f32_e32 v47, v47
	s_nop 0
	v_mul_f32_e32 v49, 0x3f317217, v47
	v_fma_f32 v49, v47, s75, -v49
	v_fmac_f32_e32 v49, 0x3377d1cf, v47
	v_fmac_f32_e32 v49, 0x3f317217, v47
	v_cmp_lt_f32_e64 s[44:45], |v47|, s74
	s_nop 1
	v_cndmask_b32_e64 v47, v47, v49, s[44:45]
	v_cndmask_b32_e32 v49, 0, v235, vcc
	v_sub_f32_e32 v47, v47, v49
	v_add_f32_e32 v99, v50, v47
	s_nop 0
	s_nop 0
	s_waitcnt vmcnt(1)
	v_mov_b32_e32 v47, v173
	v_lshlrev_b32_e32 v47, 16, v47
	v_mul_f32_e32 v47, 0xbfb8aa3b, v47
	s_waitcnt vmcnt(0)
	v_mov_b32_e32 v49, v174
	v_lshlrev_b32_e32 v100, 16, v49
	v_exp_f32_e32 v49, v47
	s_nop 0
	v_add_f32_e32 v47, 1.0, v49
	v_rcp_f32_e32 v47, v47
	s_nop 0
	v_fmac_f32_e32 v51, v0, v47
	v_cmp_gt_f32_e32 vcc, s60, v51
	s_nop 1
	v_cndmask_b32_e64 v53, 0, 32, vcc
	v_ldexp_f32 v51, v51, v53
	v_log_f32_e32 v51, v51
	s_nop 0
	v_mul_f32_e32 v53, 0x3f317217, v51
	v_fma_f32 v53, v51, s75, -v53
	v_fmac_f32_e32 v53, 0x3377d1cf, v51
	v_fmac_f32_e32 v53, 0x3f317217, v51
	v_cmp_lt_f32_e64 s[44:45], |v51|, s74
	s_nop 1
	v_cndmask_b32_e64 v51, v51, v53, s[44:45]
	v_cndmask_b32_e32 v53, 0, v235, vcc
	v_sub_f32_e32 v51, v51, v53
	v_add_f32_e32 v51, v99, v51
	ds_write_b32 v58, v51 offset:17408
	s_waitcnt lgkmcnt(0)
	s_barrier
	ds_read2st64_b32 v[54:55], v18 offset0:68 offset1:70
	s_waitcnt lgkmcnt(0)
	v_cndmask_b32_e64 v53, v54, 0, s[4:5]
	v_add_f32_e32 v101, v57, v53
	v_mul_f32_e32 v57, 0xbfb8aa3b, v56
	v_exp_f32_e32 v57, v57
	v_add_f32_e32 v86, v86, v53
	v_mul_f32_e32 v103, 0x3fb8aa3b, v86
	v_exp_f32_e32 v103, v103
	v_add_f32_e32 v57, 1.0, v57
	v_rcp_f32_e32 v57, v57
	v_mul_f32_e32 v79, v79, v103
	v_bfe_u32 v103, v79, 16, 1
	v_mul_f32_e32 v56, v57, v56
	v_mul_f32_e32 v57, 0x3fb8aa3b, v101
	v_exp_f32_e32 v57, v57
	v_add3_u32 v79, v79, v103, s33
	v_min_f32_e64 v103, -v86, s9
	v_mul_f32_e32 v103, 0x3fb8aa3b, v103
	v_mul_f32_e32 v56, v56, v57
	v_bfe_u32 v57, v56, 16, 1
	v_add3_u32 v56, v56, v57, s33
	v_lshrrev_b32_e32 v102, 16, v56
	v_lshl_add_u64 v[56:57], s[2:3], 0, v[28:29]
	global_store_short v[56:57], v102, off offset:-1792
	ds_write_b16 v60, v102
	v_min_f32_e64 v102, -v101, s9
	v_mul_f32_e32 v102, 0x3fb8aa3b, v102
	v_exp_f32_e32 v102, v102
	v_exp_f32_e32 v103, v103
	v_lshrrev_b32_e32 v79, 16, v79
	global_store_short v[56:57], v79, off offset:-1536
	v_mul_f32_e32 v8, v6, v102
	v_bfe_u32 v9, v8, 16, 1
	v_add3_u32 v8, v8, v9, s33
	ds_write_b16_d16_hi v60, v8 offset:8704
	ds_write_b16 v61, v79
	v_mul_f32_e32 v8, v7, v103
	v_bfe_u32 v9, v8, 16, 1
	v_add3_u32 v8, v8, v9, s33
	ds_write_b16_d16_hi v61, v8 offset:8704
	v_mul_f32_e32 v8, 0xbfb8aa3b, v83
	v_exp_f32_e32 v8, v8
	v_add_f32_e32 v79, v89, v53
	v_mul_f32_e32 v9, 0x3fb8aa3b, v79
	v_exp_f32_e32 v9, v9
	v_add_f32_e32 v8, 1.0, v8
	v_rcp_f32_e32 v8, v8
	s_nop 0
	v_mul_f32_e32 v8, v8, v83
	v_mul_f32_e32 v8, v8, v9
	v_bfe_u32 v9, v8, 16, 1
	v_add3_u32 v8, v8, v9, s33
	v_lshrrev_b32_e32 v8, 16, v8
	global_store_short v[56:57], v8, off offset:-1280
	ds_write_b16 v62, v8
	v_min_f32_e64 v8, -v79, s9
	v_mul_f32_e32 v8, 0x3fb8aa3b, v8
	v_exp_f32_e32 v89, v8
	v_mul_f32_e32 v8, 0xbfb8aa3b, v88
	v_exp_f32_e32 v8, v8
	v_add_f32_e32 v83, v92, v53
	v_mul_f32_e32 v9, 0x3fb8aa3b, v83
	v_exp_f32_e32 v9, v9
	v_add_f32_e32 v8, 1.0, v8
	v_rcp_f32_e32 v8, v8
	s_nop 0
	v_mul_f32_e32 v8, v8, v88
	v_mul_f32_e32 v8, v8, v9
	v_bfe_u32 v9, v8, 16, 1
	v_add3_u32 v8, v8, v9, s33
	v_lshrrev_b32_e32 v88, 16, v8
	v_min_f32_e64 v8, -v83, s9
	v_mul_f32_e32 v8, 0x3fb8aa3b, v8
	v_exp_f32_e32 v92, v8
	v_pk_mul_f32 v[8:9], v[0:1], v[36:37] op_sel_hi:[0,1]
	v_pk_mul_f32 v[8:9], v[8:9], v[34:35]
	global_store_short v[56:57], v88, off offset:-1024
	v_mul_f32_e32 v34, v8, v89
	v_bfe_u32 v35, v34, 16, 1
	v_add3_u32 v34, v34, v35, s33
	ds_write_b16_d16_hi v62, v34 offset:8704
	ds_write_b16 v63, v88
	v_mul_f32_e32 v34, v9, v92
	v_bfe_u32 v35, v34, 16, 1
	v_add3_u32 v34, v34, v35, s33
	ds_write_b16_d16_hi v63, v34 offset:8704
	v_mul_f32_e32 v34, 0xbfb8aa3b, v81
	v_exp_f32_e32 v34, v34
	v_add_f32_e32 v36, v87, v53
	v_mul_f32_e32 v35, 0x3fb8aa3b, v36
	v_exp_f32_e32 v35, v35
	v_add_f32_e32 v34, 1.0, v34
	v_rcp_f32_e32 v34, v34
	v_add_f32_e32 v37, v82, v53
	v_mul_f32_e32 v34, v34, v81
	v_mul_f32_e32 v34, v34, v35
	v_bfe_u32 v35, v34, 16, 1
	v_add3_u32 v34, v34, v35, s33
	v_mul_f32_e32 v35, 0xbfb8aa3b, v77
	v_exp_f32_e32 v35, v35
; DEVI bf16_t f2bf(float f) { uint32_t u = __float_as_uint(f); u += 0x7fffu + ((u >> 16) & 1u); return (bf16_t)(u >> 16); }
; DEVI void phase_p2(const int TIDX, const int BIDX, const int GDIM, KAP KA, unsigned char* WSB, float* OUTB, int l, unsigned char* smem) {
;     ...
;         for (int j = 0; j < 16; ++j) {
;           const int t = half * 16 + j;
;           const float b = bt[j] + off;
;           const float qs = qv[j] * __builtin_amdgcn_rcpf(1.f + __expf(-qv[j]));
;           const bf16_t qt = f2bf(qs * __expf(b));
;           QT[((size_t)cid * 32 + t) * 128 + k] = qt;
;           sQ[t * 136 + k] = qt;
;           sK[t * 136 + k] = f2bf(kk[j] * __expf(fminf(-b, 80.f)));
;           bt[j] = kk[j] * __expf(bend - b);
	v_lshrrev_b32_e32 v34, 16, v34
	global_store_short v[56:57], v34, off offset:-768
	ds_write_b16 v64, v34
	v_add_f32_e32 v35, 1.0, v35
	v_rcp_f32_e32 v35, v35
	v_min_f32_e64 v34, -v36, s9
	v_mul_f32_e32 v34, 0x3fb8aa3b, v34
	v_exp_f32_e32 v34, v34
	v_mul_f32_e32 v35, v35, v77
	v_mul_f32_e32 v77, 0x3fb8aa3b, v37
	v_exp_f32_e32 v77, v77
	v_mul_f32_e32 v32, v14, v34
	v_bfe_u32 v33, v32, 16, 1
	v_add3_u32 v32, v32, v33, s33
	v_mul_f32_e32 v35, v35, v77
	v_bfe_u32 v77, v35, 16, 1
	v_add3_u32 v35, v35, v77, s33
	v_min_f32_e64 v77, -v37, s9
	v_mul_f32_e32 v77, 0x3fb8aa3b, v77
	v_exp_f32_e32 v77, v77
	v_lshrrev_b32_e32 v35, 16, v35
	global_store_short v[56:57], v35, off offset:-512
	ds_write_b16_d16_hi v64, v32 offset:8704
	ds_write_b16 v65, v35
	v_mul_f32_e32 v32, v15, v77
	v_bfe_u32 v33, v32, 16, 1
	v_add3_u32 v32, v32, v33, s33
	ds_write_b16_d16_hi v65, v32 offset:8704
	v_mul_f32_e32 v32, 0xbfb8aa3b, v95
	v_exp_f32_e32 v32, v32
	v_add_f32_e32 v77, v97, v53
	v_mul_f32_e32 v33, 0x3fb8aa3b, v77
	v_exp_f32_e32 v33, v33
	v_add_f32_e32 v32, 1.0, v32
	v_rcp_f32_e32 v32, v32
	v_add_f32_e32 v81, v96, v53
	v_mul_f32_e32 v32, v32, v95
	v_mul_f32_e32 v32, v32, v33
	v_bfe_u32 v33, v32, 16, 1
	v_add3_u32 v32, v32, v33, s33
	v_lshrrev_b32_e32 v32, 16, v32
	global_store_short v[56:57], v32, off offset:-256
	ds_write_b16 v66, v32
	v_min_f32_e64 v32, -v77, s9
	v_mul_f32_e32 v32, 0x3fb8aa3b, v32
	v_exp_f32_e32 v34, v32
	v_mul_f32_e32 v32, 0xbfb8aa3b, v94
	v_exp_f32_e32 v32, v32
	v_mul_f32_e32 v33, 0x3fb8aa3b, v81
	v_exp_f32_e32 v33, v33
	v_add_f32_e32 v32, 1.0, v32
	v_rcp_f32_e32 v32, v32
	s_nop 0
	v_mul_f32_e32 v32, v32, v94
	v_mul_f32_e32 v32, v32, v33
	v_bfe_u32 v33, v32, 16, 1
	v_add3_u32 v32, v32, v33, s33
	v_lshrrev_b32_e32 v35, 16, v32
	v_min_f32_e64 v32, -v81, s9
	v_mul_f32_e32 v32, 0x3fb8aa3b, v32
	v_exp_f32_e32 v82, v32
	v_pk_mul_f32 v[32:33], v[0:1], v[44:45] op_sel_hi:[0,1]
	v_pk_mul_f32 v[32:33], v[32:33], v[42:43]
	global_store_short v[56:57], v35, off
	v_mul_f32_e32 v34, v32, v34
	v_bfe_u32 v42, v34, 16, 1
	v_add3_u32 v34, v34, v42, s33
	ds_write_b16_d16_hi v66, v34 offset:8704
	ds_write_b16 v67, v35
	v_mul_f32_e32 v34, v33, v82
	v_bfe_u32 v35, v34, 16, 1
	v_add3_u32 v34, v34, v35, s33
	ds_write_b16_d16_hi v67, v34 offset:8704
	v_mul_f32_e32 v34, 0xbfb8aa3b, v90
	v_exp_f32_e32 v34, v34
	v_add_f32_e32 v42, v93, v53
	v_mul_f32_e32 v35, 0x3fb8aa3b, v42
	v_exp_f32_e32 v35, v35
	v_add_f32_e32 v34, 1.0, v34
	v_rcp_f32_e32 v34, v34
	v_add_f32_e32 v43, v91, v53
	v_mul_f32_e32 v34, v34, v90
	v_mul_f32_e32 v34, v34, v35
	v_bfe_u32 v35, v34, 16, 1
	v_add3_u32 v34, v34, v35, s33
	v_lshrrev_b32_e32 v34, 16, v34
	global_store_short v[56:57], v34, off offset:256
	ds_write_b16 v68, v34
	v_min_f32_e64 v34, -v42, s9
	v_mul_f32_e32 v34, 0x3fb8aa3b, v34
	v_exp_f32_e32 v44, v34
	v_mul_f32_e32 v34, 0xbfb8aa3b, v84
	v_exp_f32_e32 v34, v34
	v_mul_f32_e32 v35, 0x3fb8aa3b, v43
	v_exp_f32_e32 v35, v35
	v_add_f32_e32 v34, 1.0, v34
	v_rcp_f32_e32 v34, v34
	s_nop 0
	v_mul_f32_e32 v34, v34, v84
	v_mul_f32_e32 v34, v34, v35
	v_bfe_u32 v35, v34, 16, 1
	v_add3_u32 v34, v34, v35, s33
	v_lshrrev_b32_e32 v45, 16, v34
	v_min_f32_e64 v34, -v43, s9
	v_mul_f32_e32 v34, 0x3fb8aa3b, v34
	v_exp_f32_e32 v82, v34
	v_pk_mul_f32 v[34:35], v[0:1], v[40:41] op_sel_hi:[0,1]
	v_pk_mul_f32 v[34:35], v[34:35], v[38:39]
	global_store_short v[56:57], v45, off offset:512
	v_mul_f32_e32 v38, v34, v44
	v_bfe_u32 v39, v38, 16, 1
	v_add3_u32 v38, v38, v39, s33
	ds_write_b16_d16_hi v68, v38 offset:8704
	ds_write_b16 v69, v45
	v_mul_f32_e32 v38, v35, v82
	v_bfe_u32 v39, v38, 16, 1
	v_add3_u32 v38, v38, v39, s33
	v_mul_f32_e32 v39, 0xbfb8aa3b, v78
	v_exp_f32_e32 v39, v39
	ds_write_b16_d16_hi v69, v38 offset:8704
	v_add_f32_e32 v38, v85, v53
	v_mul_f32_e32 v40, 0x3fb8aa3b, v38
	v_add_f32_e32 v39, 1.0, v39
	v_rcp_f32_e32 v39, v39
	v_exp_f32_e32 v40, v40
	v_mul_f32_e32 v41, 0xbfb8aa3b, v76
	v_exp_f32_e32 v41, v41
	v_mul_f32_e32 v39, v39, v78
; DEVI bf16_t f2bf(float f) { uint32_t u = __float_as_uint(f); u += 0x7fffu + ((u >> 16) & 1u); return (bf16_t)(u >> 16); }
; DEVI uint32_t pack2(float lo, float hi) { f32x2_t v = {lo, hi}; bf16x2_t b = __builtin_convertvector(v, bf16x2_t); return __builtin_bit_cast(uint32_t, b); }
; DEVI void phase_p2(const int TIDX, const int BIDX, const int GDIM, KAP KA, unsigned char* WSB, float* OUTB, int l, unsigned char* smem) {
;     ...
;         for (int j = 0; j < 16; ++j) {
;           const int t = half * 16 + j;
;           const float b = bt[j] + off;
;           const float qs = qv[j] * __builtin_amdgcn_rcpf(1.f + __expf(-qv[j]));
;           const bf16_t qt = f2bf(qs * __expf(b));
;           QT[((size_t)cid * 32 + t) * 128 + k] = qt;
;           sQ[t * 136 + k] = qt;
;           sK[t * 136 + k] = f2bf(kk[j] * __expf(fminf(-b, 80.f)));
;           bt[j] = kk[j] * __expf(bend - b);
;         }
; #pragma unroll
;         for (int j = 0; j < 8; ++j) pk[j] = pack2(bt[2 * j], bt[2 * j + 1]);
;         if (half == 0) EBp[(size_t)cid * 128 + k] = __expf(bend);
	v_mul_f32_e32 v39, v39, v40
	v_bfe_u32 v40, v39, 16, 1
	v_add3_u32 v39, v39, v40, s33
	v_lshrrev_b32_e32 v39, 16, v39
	global_store_short v[56:57], v39, off offset:768
	ds_write_b16 v70, v39
	v_min_f32_e64 v39, -v38, s9
	v_mul_f32_e32 v39, 0x3fb8aa3b, v39
	v_exp_f32_e32 v40, v39
	v_add_f32_e32 v39, v80, v53
	v_add_f32_e32 v41, 1.0, v41
	v_rcp_f32_e32 v41, v41
	v_mul_f32_e32 v44, 0x3fb8aa3b, v39
	v_exp_f32_e32 v44, v44
	v_mul_f32_e32 v12, v10, v40
	v_mul_f32_e32 v41, v41, v76
	v_bfe_u32 v13, v12, 16, 1
	v_mul_f32_e32 v41, v41, v44
	v_bfe_u32 v44, v41, 16, 1
	v_add3_u32 v41, v41, v44, s33
	v_min_f32_e64 v44, -v39, s9
	v_mul_f32_e32 v44, 0x3fb8aa3b, v44
	v_exp_f32_e32 v44, v44
	v_lshrrev_b32_e32 v41, 16, v41
	v_add3_u32 v12, v12, v13, s33
	global_store_short v[56:57], v41, off offset:1024
	ds_write_b16_d16_hi v70, v12 offset:8704
	ds_write_b16 v71, v41
	v_mul_f32_e32 v12, v11, v44
	v_bfe_u32 v13, v12, 16, 1
	v_add3_u32 v12, v12, v13, s33
	v_mul_f32_e32 v13, 0xbfb8aa3b, v19
	v_exp_f32_e32 v13, v13
	ds_write_b16_d16_hi v71, v12 offset:8704
	v_add_f32_e32 v12, v52, v53
	v_mul_f32_e32 v40, 0xbfb8aa3b, v1
	v_add_f32_e32 v13, 1.0, v13
	v_rcp_f32_e32 v13, v13
	v_exp_f32_e32 v40, v40
	v_mov_b32_e32 v52, v54
	v_mul_f32_e32 v13, v13, v19
	v_mul_f32_e32 v19, 0x3fb8aa3b, v12
	v_exp_f32_e32 v19, v19
	v_add_f32_e32 v40, 1.0, v40
	v_rcp_f32_e32 v40, v40
	v_mul_f32_e32 v13, v13, v19
	v_bfe_u32 v19, v13, 16, 1
	v_add3_u32 v13, v13, v19, s33
	v_lshrrev_b32_e32 v13, 16, v13
	global_store_short v[56:57], v13, off offset:1280
	ds_write_b16 v72, v13
	v_min_f32_e64 v13, -v12, s9
	v_mul_f32_e32 v13, 0x3fb8aa3b, v13
	v_exp_f32_e32 v19, v13
	v_add_f32_e32 v13, v53, v50
	v_mul_f32_e32 v1, v40, v1
	v_mul_f32_e32 v40, 0x3fb8aa3b, v13
	v_exp_f32_e32 v40, v40
	v_mov_b32_e32 v50, v55
	v_mul_f32_e32 v1, v1, v40
	v_bfe_u32 v40, v1, 16, 1
	v_add3_u32 v1, v1, v40, s33
	v_lshrrev_b32_e32 v1, 16, v1
	v_min_f32_e64 v40, -v13, s9
	v_mul_f32_e32 v40, 0x3fb8aa3b, v40
	v_pk_mul_f32 v[4:5], v[0:1], v[4:5] op_sel_hi:[0,1]
	v_exp_f32_e32 v40, v40
	v_pk_mul_f32 v[2:3], v[4:5], v[2:3]
	global_store_short v[56:57], v1, off offset:1536
	v_mul_f32_e32 v4, v2, v19
	v_bfe_u32 v5, v4, 16, 1
	v_add3_u32 v4, v4, v5, s33
	ds_write_b16_d16_hi v72, v4 offset:8704
	ds_write_b16 v73, v1
	v_mul_f32_e32 v1, v3, v40
	v_bfe_u32 v4, v1, 16, 1
	v_add3_u32 v1, v1, v4, s33
	ds_write_b16_d16_hi v73, v1 offset:8704
	v_mul_f32_e32 v1, 0xbfb8aa3b, v98
	v_exp_f32_e32 v1, v1
	v_add_f32_e32 v19, v53, v99
	v_mul_f32_e32 v4, 0x3fb8aa3b, v19
	v_exp_f32_e32 v4, v4
	v_add_f32_e32 v1, 1.0, v1
	v_rcp_f32_e32 v1, v1
	s_nop 0
	v_mul_f32_e32 v1, v1, v98
	v_mul_f32_e32 v1, v1, v4
	v_bfe_u32 v4, v1, 16, 1
	v_add3_u32 v1, v1, v4, s33
	v_lshrrev_b32_e32 v1, 16, v1
	global_store_short v[56:57], v1, off offset:1792
	ds_write_b16 v74, v1
	v_min_f32_e64 v1, -v19, s9
	v_mul_f32_e32 v1, 0x3fb8aa3b, v1
	v_exp_f32_e32 v44, v1
	v_mul_f32_e32 v1, 0xbfb8aa3b, v100
	v_exp_f32_e32 v1, v1
	v_pk_add_f32 v[4:5], v[52:53], v[50:51]
	v_add_f32_e32 v1, 1.0, v1
	v_rcp_f32_e32 v1, v1
	v_mul_f32_e32 v40, 0x3fb8aa3b, v5
	v_exp_f32_e32 v40, v40
	v_mul_f32_e32 v1, v1, v100
	v_mul_f32_e32 v1, v1, v40
	v_bfe_u32 v40, v1, 16, 1
	v_add3_u32 v1, v1, v40, s33
	v_lshrrev_b32_e32 v45, 16, v1
	v_min_f32_e64 v1, -v5, s9
	v_lshl_add_u64 v[40:41], s[2:3], 0, v[26:27]
	v_mul_f32_e32 v1, 0x3fb8aa3b, v1
	global_store_short v[40:41], v45, off
	v_exp_f32_e32 v40, v1
	v_pk_mul_f32 v[0:1], v[0:1], v[48:49] op_sel_hi:[0,1]
	v_pk_mul_f32 v[0:1], v[0:1], v[46:47]
	s_nop 0
	v_mul_f32_e32 v41, v0, v44
	v_bfe_u32 v44, v41, 16, 1
	v_add3_u32 v41, v41, v44, s33
	v_mul_f32_e32 v40, v1, v40
	ds_write_b16_d16_hi v74, v41 offset:8704
	ds_write_b16 v75, v45
	v_bfe_u32 v41, v40, 16, 1
	v_add3_u32 v40, v40, v41, s33
	ds_write_b16_d16_hi v75, v40 offset:8704
	s_and_saveexec_b64 s[44:45], s[4:5]
	s_cbranch_execz .LBB0_382
	v_mul_f32_e32 v40, 0x3fb8aa3b, v4
	v_exp_f32_e32 v40, v40
	global_store_dword v[22:23], v40, off
